# dilated combine loop: value loads issued together with the LSE loads (one round trip per iteration instead of two)
# speedup vs baseline: 1.0080x; 1.0004x over previous
.LBB0_842:
	v_ashrrev_i32_e32 v0, 5, v5
	v_bfe_u32 v7, v5, 3, 2
	v_mad_i64_i32 v[2:3], s[12:13], v0, 48, s[6:7]
	v_lshlrev_b32_e32 v232, 2, v7
	v_lshl_add_u64 v[2:3], v[2:3], 0, v[232:233]
	global_load_dword v4, v[2:3], off
	global_load_dword v8, v[2:3], off offset:16
	s_nop 0
	global_load_dword v2, v[2:3], off offset:32
	v_ashrrev_i32_e32 v1, 31, v0
	v_lshlrev_b64 v[176:177], 13, v[0:1]
	v_lshl_add_u64 v[176:177], s[0:1], 0, v[176:177]
	v_lshlrev_b32_e32 v178, 7, v7
	v_mov_b32_e32 v179, v233
	v_lshl_add_u64 v[176:177], v[176:177], 0, v[178:179]
	v_and_b32_e32 v178, 56, v6
	v_lshlrev_b32_e32 v178, 1, v178
	v_lshl_add_u64 v[176:177], v[176:177], 0, v[178:179]
	v_add_co_u32_e32 v192, vcc, 0x7a00d40, v176
	s_nop 1
	v_addc_co_u32_e32 v193, vcc, 0, v177, vcc
	global_load_dwordx4 v[180:183], v[192:193], off
	global_load_dwordx4 v[184:187], v[192:193], off offset:512
	global_load_dwordx4 v[188:191], v[192:193], off offset:1024
	v_lshlrev_b32_e32 v232, 7, v7
	v_mov_b32_e32 v25, v233
	s_waitcnt vmcnt(0) lgkmcnt(0)
	v_max3_f32 v3, v4, v8, v2
	v_sub_f32_e32 v4, v4, v3
	v_exp_f32_e32 v21, v4
	v_sub_f32_e32 v4, v8, v3
	v_exp_f32_e32 v20, v4
	v_sub_f32_e32 v2, v2, v3
	v_exp_f32_e32 v2, v2
	v_add_f32_e32 v3, v21, v20
	v_add_f32_e32 v3, v2, v3
	v_div_scale_f32 v4, s[12:13], v3, v3, 1.0
	v_rcp_f32_e32 v8, v4
	s_mov_b64 s[12:13], 0x7a00d40
	v_fma_f32 v9, -v4, v8, 1.0
	v_fmac_f32_e32 v8, v9, v8
	v_div_scale_f32 v9, vcc, 1.0, v3, 1.0
	v_mul_f32_e32 v10, v9, v8
	v_fma_f32 v11, -v4, v10, v9
	v_fmac_f32_e32 v10, v11, v8
	v_fma_f32 v4, -v4, v10, v9
	v_div_fmas_f32 v4, v4, v8, v10
	v_div_fixup_f32 v22, v4, v3, 1.0
	v_mul_f32_e32 v4, v2, v22
	v_lshlrev_b64 v[2:3], 13, v[0:1]
	v_lshl_add_u64 v[2:3], s[0:1], 0, v[2:3]
	v_and_b32_e32 v1, 56, v6
	v_lshl_add_u64 v[8:9], v[2:3], 0, v[232:233]
	v_lshlrev_b32_e32 v24, 1, v1
	v_lshl_add_u64 v[8:9], v[8:9], 0, v[24:25]
	v_lshl_add_u64 v[16:17], v[8:9], 0, s[12:13]
	s_mov_b32 s12, 0x7a00000
	v_add_co_u32_e32 v8, vcc, s12, v8
	v_pk_mul_f32 v[20:21], v[20:21], v[22:23] op_sel_hi:[1,0]
	s_nop 0
	v_addc_co_u32_e32 v9, vcc, 0, v9, vcc
	s_nop 0
	s_nop 0
	v_mad_i64_i32 v[0:1], s[12:13], v0, s46, v[2:3]
	v_lshl_add_u64 v[0:1], v[0:1], 0, v[232:233]
	v_lshl_add_u64 v[0:1], v[0:1], 0, v[24:25]
	v_add_co_u32_e32 v0, vcc, 0x17a00000, v0
	v_add_u32_e32 v6, s11, v6
	s_nop 0
	v_addc_co_u32_e32 v1, vcc, 0, v1, vcc
	v_lshlrev_b32_e32 v26, 16, v180
	v_and_b32_e32 v27, 0xffff0000, v184
	v_lshlrev_b32_e32 v22, 16, v184
	v_and_b32_e32 v23, 0xffff0000, v180
	v_pk_mul_f32 v[26:27], v[20:21], v[26:27] op_sel:[1,0] op_sel_hi:[0,1]
	v_lshlrev_b32_e32 v28, 16, v188
	v_and_b32_e32 v29, 0xffff0000, v188
	v_pk_fma_f32 v[22:23], v[20:21], v[22:23], v[26:27]
	v_lshlrev_b32_e32 v12, 16, v181
	v_pk_fma_f32 v[22:23], v[4:5], v[28:29], v[22:23] op_sel_hi:[0,1,1]
	v_cvt_pk_bf16_f32 v8, v22, v23
	v_lshlrev_b32_e32 v22, 16, v185
	v_and_b32_e32 v13, 0xffff0000, v185
	v_and_b32_e32 v23, 0xffff0000, v181
	v_pk_mul_f32 v[12:13], v[20:21], v[12:13] op_sel:[1,0] op_sel_hi:[0,1]
	v_lshlrev_b32_e32 v16, 16, v189
	v_and_b32_e32 v17, 0xffff0000, v189
	v_pk_fma_f32 v[12:13], v[20:21], v[22:23], v[12:13]
	v_lshlrev_b32_e32 v22, 16, v190
	v_pk_fma_f32 v[12:13], v[4:5], v[16:17], v[12:13] op_sel_hi:[0,1,1]
	v_lshlrev_b32_e32 v16, 16, v182
	v_and_b32_e32 v17, 0xffff0000, v186
	v_cvt_pk_bf16_f32 v9, v12, v13
	v_lshlrev_b32_e32 v12, 16, v186
	v_and_b32_e32 v13, 0xffff0000, v182
	v_pk_mul_f32 v[16:17], v[20:21], v[16:17] op_sel:[1,0] op_sel_hi:[0,1]
	v_and_b32_e32 v23, 0xffff0000, v190
	v_pk_fma_f32 v[12:13], v[20:21], v[12:13], v[16:17]
	v_lshlrev_b32_e32 v14, 16, v183
	v_pk_fma_f32 v[12:13], v[4:5], v[22:23], v[12:13] op_sel_hi:[0,1,1]
	v_cvt_pk_bf16_f32 v10, v12, v13
	v_lshlrev_b32_e32 v12, 16, v187
	v_and_b32_e32 v15, 0xffff0000, v187
	v_and_b32_e32 v13, 0xffff0000, v183
	v_pk_mul_f32 v[14:15], v[20:21], v[14:15] op_sel:[1,0] op_sel_hi:[0,1]
	v_pk_fma_f32 v[12:13], v[20:21], v[12:13], v[14:15]
	v_lshlrev_b32_e32 v14, 16, v191
	v_and_b32_e32 v15, 0xffff0000, v191
	v_pk_fma_f32 v[12:13], v[4:5], v[14:15], v[12:13] op_sel_hi:[0,1,1]
	v_add_u32_e32 v5, s10, v5
	v_cmp_lt_i32_e32 vcc, s14, v5
	v_cvt_pk_bf16_f32 v11, v12, v13
	s_or_b64 s[8:9], vcc, s[8:9]
	global_store_dwordx4 v[0:1], v[8:11], off offset:1536
	s_andn2_b64 exec, exec, s[8:9]
	s_cbranch_execnz .LBB0_842
